# P0 weight-copy items rebalanced: workgroups that own an adaLN modulation item take one copy item, the others two or three
# speedup vs baseline: 1.0050x; 1.0050x over previous
.LBB0_44:
	s_cmpk_lt_u32 s98, 0x800
	s_cbranch_scc0 .Lp0_r3
	s_bfe_u32 s14, s80, 0x50003
	s_cmpk_lt_u32 s14, 12
	s_cbranch_scc1 .LBB0_83
	s_lshr_b32 s99, s80, 8
	s_mulk_i32 s99, 20
	s_add_i32 s99, s99, s14
	s_sub_i32 s99, s99, 12
	s_lshl_b32 s99, s99, 3
	s_and_b32 s14, s80, 7
	s_add_i32 s99, s99, s14
	s_add_i32 s98, s99, 0x800
	s_branch .Lp0_item
.Lp0_r3:
	s_addk_i32 s98, 0x500
	s_cmpk_gt_i32 s98, 0x107f
	s_cbranch_scc1 .LBB0_83
.Lp0_item:
	s_cmpk_lt_i32 s98, 0x880
	s_cselect_b32 s14, 0, 0xc00
	s_add_i32 s14, s14, s98
